# GEMM1 transposed epilogue (retention-K group): zeta factors exp2(l2g*(z-j)) computed once per (bj,ai) and reused in the other three mi blocks instead of recomputed in all 16 blocks
# speedup vs baseline: 1.0424x; 1.0073x over previous
.LBB0_130:
	v_bitop3_b32 v177, v160, 47, 44 bitop3:0x6c
	v_cndmask_b32_e64 v178, 0, 1, s[44:45]
	v_cmp_ne_u32_e64 s[42:43], 1, v178
	v_cvt_f32_ubyte0_e32 v191, v177
	v_add_u32_e32 v178, -1, v177
	v_add_u32_e32 v182, -2, v177
	v_add_u32_e32 v177, -3, v177
	v_cvt_f32_u32_e32 v189, v178
	v_cvt_f32_u32_e32 v186, v182
	v_cvt_f32_u32_e32 v182, v177
	v_and_b32_e32 v173, 44, v160
	v_bitop3_b32 v176, v160, 63, 44 bitop3:0x6c
	s_lshl_b32 s11, s76, 8
	v_cvt_f32_ubyte0_e32 v192, v176
	v_sub_u32_e32 v176, 62, v173
	v_sub_u32_e32 v179, 61, v173
	v_sub_u32_e32 v173, 60, v173
	s_add_i32 s11, s11, s38
	v_pk_mul_f32 v[160:161], v[130:131], v[152:153]
	v_pk_mul_f32 v[162:163], v[132:133], v[156:157]
	v_pk_mul_f32 v[164:165], v[126:127], v[154:155]
	v_pk_mul_f32 v[166:167], v[128:129], v[158:159]
	s_andn2_b64 vcc, exec, s[44:45]
	v_cvt_f32_ubyte0_e32 v190, v176
	v_cvt_f32_ubyte0_e32 v188, v179
	v_cvt_f32_ubyte0_e32 v185, v173
	s_cbranch_vccnz .LBB0_132
	s_add_i32 s22, s11, 0xfffffc00
	s_ashr_i32 s22, s22, 7
	v_cvt_f32_i32_e32 v173, s22
	v_sub_f32_e32 v173, 0xc0a00000, v173
	v_cmp_gt_f32_e32 vcc, s9, v173
	s_and_b64 s[22:23], vcc, exec
	s_cselect_b32 s22, 0xffffffc0, 0
	v_cndmask_b32_e32 v176, 0, v200, vcc
	v_add_f32_e32 v173, v173, v176
	v_exp_f32_e32 v173, v173
	s_nop 0
	v_ldexp_f32 v173, v173, s22
	v_sub_f32_e32 v173, 1.0, v173
	v_cmp_gt_f32_e32 vcc, s7, v173
	s_and_b64 s[22:23], vcc, exec
	s_cselect_b32 s22, 32, 0
	v_ldexp_f32 v173, v173, s22
	v_log_f32_e32 v173, v173
	v_cndmask_b32_e32 v176, 0, v201, vcc
	v_sub_f32_e32 v173, v173, v176
	v_mul_f32_e32 v176, v173, v192
	v_mul_f32_e32 v177, v173, v191
	v_cmp_gt_f32_e32 vcc, s9, v176
	v_cmp_gt_f32_e64 s[48:49], s9, v177
	v_mul_f32_e32 v184, v173, v186
	v_cndmask_b32_e32 v176, 0, v200, vcc
	v_cndmask_b32_e64 v177, 0, v200, s[48:49]
	v_fmac_f32_e32 v176, v173, v192
	v_fmac_f32_e32 v177, v173, v191
	v_exp_f32_e32 v176, v176
	v_exp_f32_e32 v177, v177
	v_cndmask_b32_e32 v178, 0, v202, vcc
	v_cndmask_b32_e64 v179, 0, v202, s[48:49]
	v_ldexp_f32 v176, v176, v178
	v_ldexp_f32 v178, v177, v179
	v_mul_f32_e32 v177, v173, v190
	v_cmp_gt_f32_e32 vcc, s9, v177
	v_mul_f32_e32 v179, v173, v189
	v_cmp_gt_f32_e64 s[48:49], s9, v179
	v_cndmask_b32_e32 v177, 0, v200, vcc
	v_fmac_f32_e32 v177, v173, v190
	v_cndmask_b32_e64 v179, 0, v200, s[48:49]
	v_exp_f32_e32 v177, v177
	v_fmac_f32_e32 v179, v173, v189
	v_exp_f32_e32 v179, v179
	v_cndmask_b32_e32 v183, 0, v202, vcc
	v_ldexp_f32 v177, v177, v183
	v_cndmask_b32_e64 v183, 0, v202, s[48:49]
	v_ldexp_f32 v179, v179, v183
	v_mul_f32_e32 v183, v173, v188
	v_cmp_gt_f32_e32 vcc, s9, v183
	v_cmp_gt_f32_e64 s[48:49], s9, v184
	v_pk_mul_f32 v[160:161], v[176:177], v[160:161]
	v_cndmask_b32_e32 v183, 0, v200, vcc
	v_fmac_f32_e32 v183, v173, v188
	v_cndmask_b32_e64 v184, 0, v200, s[48:49]
	v_exp_f32_e32 v183, v183
	v_fmac_f32_e32 v184, v173, v186
	v_exp_f32_e32 v184, v184
	v_cndmask_b32_e32 v187, 0, v202, vcc
	v_ldexp_f32 v194, v183, v187
	v_cndmask_b32_e64 v183, 0, v202, s[48:49]
	v_ldexp_f32 v208, v184, v183
	v_mul_f32_e32 v183, v173, v185
	v_cmp_gt_f32_e32 vcc, s9, v183
	v_mul_f32_e32 v184, v173, v182
	v_cmp_gt_f32_e64 s[48:49], s9, v184
	v_cndmask_b32_e32 v183, 0, v200, vcc
	v_fmac_f32_e32 v183, v173, v185
	v_cndmask_b32_e64 v184, 0, v200, s[48:49]
	v_exp_f32_e32 v183, v183
	v_fmac_f32_e32 v184, v173, v182
	v_exp_f32_e32 v173, v184
	v_cndmask_b32_e32 v184, 0, v202, vcc
	v_ldexp_f32 v195, v183, v184
	v_cndmask_b32_e64 v183, 0, v202, s[48:49]
	v_ldexp_f32 v209, v173, v183
	v_pk_mul_f32 v[162:163], v[194:195], v[162:163]
	v_pk_mul_f32 v[164:165], v[178:179], v[164:165]
	v_pk_mul_f32 v[166:167], v[208:209], v[166:167]
	v_mov_b32_e32 v216, v176
	v_mov_b32_e32 v217, v177
	v_mov_b32_e32 v218, v194
	v_mov_b32_e32 v219, v195
	v_mov_b32_e32 v220, v178
	v_mov_b32_e32 v221, v179
	v_mov_b32_e32 v222, v208
	v_mov_b32_e32 v223, v209
.LBB0_132:
	s_cmp_eq_u32 s5, 2
	s_movk_i32 s22, 0x800
	v_cvt_pk_bf16_f32 v160, v160, v161
	v_cvt_pk_bf16_f32 v161, v162, v163
	v_cvt_pk_bf16_f32 v162, v164, v165
	v_lshlrev_b32_e32 v164, 2, v171
	s_cselect_b32 s31, 0x400, s22
	s_and_b64 s[22:23], s[44:45], exec
	v_and_b32_e32 v173, 3, v0
	v_and_b32_e32 v184, 16, v164
	v_lshrrev_b32_e32 v0, 1, v0
	s_cselect_b32 s22, 0, s31
	s_lshl_b32 s23, s5, 10
	v_and_or_b32 v183, v0, 4, v184
	s_sub_i32 s22, s22, s23
	s_mulk_i32 s18, 0xc00
	v_or_b32_e32 v177, s11, v171
	v_or3_b32 v0, v173, s11, v183
	s_add_i32 s33, s22, s18
	v_cndmask_b32_e64 v176, v177, v0, s[44:45]
	v_add_u32_e32 v0, s33, v176
	s_ashr_i32 s31, s30, 31
	v_mad_i64_i32 v[164:165], s[48:49], v0, s80, v[134:135]
	v_lshl_add_u64 v[164:165], s[30:31], 1, v[164:165]
	v_lshlrev_b32_e32 v0, 4, v172
	v_cvt_pk_bf16_f32 v163, v166, v167
	v_lshl_add_u64 v[164:165], v[164:165], 0, v[0:1]
	global_store_dwordx4 v[164:165], v[160:163], off
	v_pk_mul_f32 v[164:165], v[120:121], v[156:157]
	s_and_b64 vcc, exec, s[42:43]
	v_pk_mul_f32 v[160:161], v[118:119], v[152:153]
	v_pk_mul_f32 v[162:163], v[110:111], v[154:155]
	v_pk_mul_f32 v[166:167], v[112:113], v[158:159]
	s_cbranch_vccnz .LBB0_134
	v_pk_mul_f32 v[160:161], v[216:217], v[160:161]
	v_pk_mul_f32 v[164:165], v[218:219], v[164:165]
	v_pk_mul_f32 v[162:163], v[220:221], v[162:163]
	v_pk_mul_f32 v[166:167], v[222:223], v[166:167]
.LBB0_134:
	v_or_b32_e32 v177, 16, v177
	v_cvt_pk_bf16_f32 v160, v160, v161
	v_cvt_pk_bf16_f32 v161, v164, v165
	v_lshrrev_b32_e32 v164, 1, v177
	v_and_or_b32 v164, v164, 12, s11
	v_or3_b32 v164, v164, v173, v184
	v_cndmask_b32_e64 v177, v177, v164, s[44:45]
	v_add_u32_e32 v164, s33, v177
	v_lshlrev_b32_e32 v0, 3, v172
	v_mad_i64_i32 v[164:165], s[48:49], v164, s80, v[134:135]
	v_lshl_add_u64 v[164:165], s[30:31], 1, v[164:165]
	v_lshlrev_b32_e32 v0, 1, v0
	v_cvt_pk_bf16_f32 v162, v162, v163
	v_cvt_pk_bf16_f32 v163, v166, v167
	v_lshl_add_u64 v[164:165], v[164:165], 0, v[0:1]
	global_store_dwordx4 v[164:165], v[160:163], off
	v_pk_mul_f32 v[164:165], v[104:105], v[156:157]
	s_and_b64 vcc, exec, s[42:43]
	v_pk_mul_f32 v[160:161], v[102:103], v[152:153]
	v_pk_mul_f32 v[162:163], v[98:99], v[154:155]
	v_pk_mul_f32 v[166:167], v[100:101], v[158:159]
	s_cbranch_vccnz .LBB0_136
	v_pk_mul_f32 v[160:161], v[216:217], v[160:161]
	v_pk_mul_f32 v[164:165], v[218:219], v[164:165]
	v_pk_mul_f32 v[162:163], v[220:221], v[162:163]
	v_pk_mul_f32 v[166:167], v[222:223], v[166:167]
.LBB0_136:
	s_or_b32 s18, s11, 32
	v_or_b32_e32 v178, s18, v171
	v_cvt_pk_bf16_f32 v160, v160, v161
	v_cvt_pk_bf16_f32 v161, v164, v165
	v_or3_b32 v164, v173, s18, v183
	v_cndmask_b32_e64 v178, v178, v164, s[44:45]
	v_add_u32_e32 v164, s33, v178
	v_mad_i64_i32 v[164:165], s[48:49], v164, s80, v[134:135]
	v_lshl_add_u64 v[164:165], s[30:31], 1, v[164:165]
	v_cvt_pk_bf16_f32 v162, v162, v163
	v_cvt_pk_bf16_f32 v163, v166, v167
	v_lshl_add_u64 v[164:165], v[164:165], 0, v[0:1]
	global_store_dwordx4 v[164:165], v[160:163], off
	v_pk_mul_f32 v[164:165], v[88:89], v[156:157]
	s_and_b64 vcc, exec, s[42:43]
	v_pk_mul_f32 v[160:161], v[86:87], v[152:153]
	v_pk_mul_f32 v[162:163], v[78:79], v[154:155]
	v_pk_mul_f32 v[166:167], v[80:81], v[158:159]
	s_cbranch_vccnz .LBB0_138
	v_pk_mul_f32 v[160:161], v[216:217], v[160:161]
	v_pk_mul_f32 v[164:165], v[218:219], v[164:165]
	v_pk_mul_f32 v[162:163], v[220:221], v[162:163]
	v_pk_mul_f32 v[166:167], v[222:223], v[166:167]
.LBB0_138:
	s_or_b32 s18, s11, 48
	v_or_b32_e32 v179, s18, v171
	v_cvt_pk_bf16_f32 v160, v160, v161
	v_cvt_pk_bf16_f32 v161, v164, v165
	s_andn2_b32 s18, s18, 31
	v_lshrrev_b32_e32 v164, 1, v179
	v_and_or_b32 v164, v164, 12, s18
	v_or3_b32 v164, v164, v173, v184
	v_cndmask_b32_e64 v179, v179, v164, s[44:45]
	v_add_u32_e32 v164, s33, v179
	v_mad_i64_i32 v[164:165], s[48:49], v164, s80, v[134:135]
	v_lshl_add_u64 v[164:165], s[30:31], 1, v[164:165]
	v_cvt_pk_bf16_f32 v162, v162, v163
	v_cvt_pk_bf16_f32 v163, v166, v167
	v_lshl_add_u64 v[164:165], v[164:165], 0, v[0:1]
	global_store_dwordx4 v[164:165], v[160:163], off
	s_add_i32 s18, s11, 0x80
	v_pk_mul_f32 v[164:165], v[68:69], v[156:157]
	v_pk_mul_f32 v[160:161], v[66:67], v[152:153]
	v_pk_mul_f32 v[162:163], v[62:63], v[154:155]
	s_and_b64 vcc, exec, s[42:43]
	v_pk_mul_f32 v[166:167], v[64:65], v[158:159]
	s_cbranch_vccnz .LBB0_140
	s_add_i32 s23, s18, 0xfffffc00
	s_ashr_i32 s23, s23, 7
	v_cvt_f32_i32_e32 v187, s23
	v_sub_f32_e32 v187, 0xc0a00000, v187
	v_cmp_gt_f32_e32 vcc, s9, v187
	s_and_b64 s[48:49], vcc, exec
	s_cselect_b32 s23, 0xffffffc0, 0
	v_cndmask_b32_e32 v193, 0, v200, vcc
	v_add_f32_e32 v187, v187, v193
	v_exp_f32_e32 v187, v187
	s_nop 0
	v_ldexp_f32 v187, v187, s23
	v_sub_f32_e32 v187, 1.0, v187
	v_cmp_gt_f32_e32 vcc, s7, v187
	s_and_b64 s[48:49], vcc, exec
	s_cselect_b32 s23, 32, 0
	v_ldexp_f32 v187, v187, s23
	v_log_f32_e32 v187, v187
	v_cndmask_b32_e32 v193, 0, v201, vcc
	v_sub_f32_e32 v187, v187, v193
	v_mul_f32_e32 v193, v187, v192
	v_mul_f32_e32 v194, v187, v191
	v_cmp_gt_f32_e32 vcc, s9, v193
	v_cmp_gt_f32_e64 s[48:49], s9, v194
	s_nop 0
	v_cndmask_b32_e32 v193, 0, v200, vcc
	v_cndmask_b32_e64 v194, 0, v200, s[48:49]
	v_fmac_f32_e32 v193, v187, v192
	v_fmac_f32_e32 v194, v187, v191
	v_exp_f32_e32 v193, v193
	v_exp_f32_e32 v195, v194
	v_cndmask_b32_e32 v194, 0, v202, vcc
	v_cndmask_b32_e64 v196, 0, v202, s[48:49]
	v_ldexp_f32 v194, v193, v194
	v_mul_f32_e32 v193, v187, v190
	v_ldexp_f32 v208, v195, v196
	v_cmp_gt_f32_e32 vcc, s9, v193
	v_mul_f32_e32 v195, v187, v189
	v_cmp_gt_f32_e64 s[48:49], s9, v195
	v_cndmask_b32_e32 v193, 0, v200, vcc
	v_fmac_f32_e32 v193, v187, v190
	v_cndmask_b32_e64 v195, 0, v200, s[48:49]
	v_exp_f32_e32 v193, v193
	v_fmac_f32_e32 v195, v187, v189
	v_exp_f32_e32 v196, v195
	v_cndmask_b32_e32 v195, 0, v202, vcc
	v_ldexp_f32 v195, v193, v195
	v_cndmask_b32_e64 v193, 0, v202, s[48:49]
	v_ldexp_f32 v209, v196, v193
	v_mul_f32_e32 v193, v187, v188
	v_cmp_gt_f32_e32 vcc, s9, v193
	v_mul_f32_e32 v196, v187, v186
	v_cmp_gt_f32_e64 s[48:49], s9, v196
	v_cndmask_b32_e32 v193, 0, v200, vcc
	v_fmac_f32_e32 v193, v187, v188
	v_cndmask_b32_e64 v196, 0, v200, s[48:49]
	v_exp_f32_e32 v193, v193
	v_fmac_f32_e32 v196, v187, v186
	v_exp_f32_e32 v196, v196
	v_cndmask_b32_e32 v197, 0, v202, vcc
	v_ldexp_f32 v210, v193, v197
	v_cndmask_b32_e64 v193, 0, v202, s[48:49]
	v_ldexp_f32 v212, v196, v193
	v_mul_f32_e32 v193, v187, v185
	v_cmp_gt_f32_e32 vcc, s9, v193
	v_mul_f32_e32 v196, v187, v182
	v_cmp_gt_f32_e64 s[48:49], s9, v196
	v_cndmask_b32_e32 v193, 0, v200, vcc
	v_fmac_f32_e32 v193, v187, v185
	v_cndmask_b32_e64 v196, 0, v200, s[48:49]
	v_exp_f32_e32 v193, v193
	v_fmac_f32_e32 v196, v187, v182
	v_exp_f32_e32 v187, v196
	v_cndmask_b32_e32 v196, 0, v202, vcc
	v_ldexp_f32 v211, v193, v196
	v_cndmask_b32_e64 v193, 0, v202, s[48:49]
	v_ldexp_f32 v213, v187, v193
	v_pk_mul_f32 v[160:161], v[194:195], v[160:161]
	v_pk_mul_f32 v[164:165], v[210:211], v[164:165]
	v_pk_mul_f32 v[162:163], v[208:209], v[162:163]
	v_pk_mul_f32 v[166:167], v[212:213], v[166:167]
	v_mov_b32_e32 v216, v194
	v_mov_b32_e32 v217, v195
	v_mov_b32_e32 v218, v210
	v_mov_b32_e32 v219, v211
	v_mov_b32_e32 v220, v208
	v_mov_b32_e32 v221, v209
	v_mov_b32_e32 v222, v212
	v_mov_b32_e32 v223, v213
.LBB0_140:
	v_or_b32_e32 v187, s18, v171
	v_cvt_pk_bf16_f32 v160, v160, v161
	v_cvt_pk_bf16_f32 v161, v164, v165
	v_or3_b32 v164, v173, s18, v183
	v_cndmask_b32_e64 v183, v187, v164, s[44:45]
	v_add_u32_e32 v164, s33, v183
	v_mad_i64_i32 v[164:165], s[48:49], v164, s80, v[134:135]
	v_lshl_add_u64 v[164:165], s[30:31], 1, v[164:165]
	v_cvt_pk_bf16_f32 v162, v162, v163
	v_cvt_pk_bf16_f32 v163, v166, v167
	v_lshl_add_u64 v[164:165], v[164:165], 0, v[0:1]
	global_store_dwordx4 v[164:165], v[160:163], off
	v_pk_mul_f32 v[164:165], v[48:49], v[156:157]
	s_and_b64 vcc, exec, s[42:43]
	v_pk_mul_f32 v[160:161], v[46:47], v[152:153]
	v_pk_mul_f32 v[162:163], v[38:39], v[154:155]
	v_pk_mul_f32 v[166:167], v[40:41], v[158:159]
	s_cbranch_vccnz .LBB0_142
	v_pk_mul_f32 v[160:161], v[216:217], v[160:161]
	v_pk_mul_f32 v[164:165], v[218:219], v[164:165]
	v_pk_mul_f32 v[162:163], v[220:221], v[162:163]
	v_pk_mul_f32 v[166:167], v[222:223], v[166:167]
.LBB0_142:
	v_or_b32_e32 v187, 16, v187
	v_cvt_pk_bf16_f32 v160, v160, v161
	v_cvt_pk_bf16_f32 v161, v164, v165
	v_lshrrev_b32_e32 v164, 1, v187
	v_and_or_b32 v164, v164, 12, s18
	v_or3_b32 v164, v164, v173, v184
	v_cndmask_b32_e64 v184, v187, v164, s[44:45]
	v_add_u32_e32 v164, s33, v184
	v_mad_i64_i32 v[164:165], s[48:49], v164, s80, v[134:135]
	v_lshl_add_u64 v[164:165], s[30:31], 1, v[164:165]
	v_cvt_pk_bf16_f32 v162, v162, v163
	v_cvt_pk_bf16_f32 v163, v166, v167
	v_lshl_add_u64 v[164:165], v[164:165], 0, v[0:1]
	global_store_dwordx4 v[164:165], v[160:163], off
	v_pk_mul_f32 v[164:165], v[24:25], v[156:157]
	s_and_b64 vcc, exec, s[42:43]
	v_pk_mul_f32 v[160:161], v[22:23], v[152:153]
	v_pk_mul_f32 v[162:163], v[14:15], v[154:155]
	v_pk_mul_f32 v[166:167], v[16:17], v[158:159]
	s_cbranch_vccnz .LBB0_144
	v_pk_mul_f32 v[160:161], v[216:217], v[160:161]
	v_pk_mul_f32 v[164:165], v[218:219], v[164:165]
	v_pk_mul_f32 v[162:163], v[220:221], v[162:163]
	v_pk_mul_f32 v[166:167], v[222:223], v[166:167]
.LBB0_144:
	s_or_b32 s23, s18, 32
	v_or_b32_e32 v187, s23, v171
	v_cvt_pk_bf16_f32 v160, v160, v161
	v_cvt_pk_bf16_f32 v161, v164, v165
	v_lshlrev_b32_e32 v164, 2, v187
	v_and_b32_e32 v164, 16, v164
	v_lshrrev_b32_e32 v165, 1, v187
	v_and_or_b32 v164, v165, 12, v164
	v_or3_b32 v164, v164, s23, v173
	v_cndmask_b32_e64 v187, v187, v164, s[44:45]
	v_add_u32_e32 v164, s33, v187
	v_mad_i64_i32 v[164:165], s[44:45], v164, s80, v[134:135]
	v_lshl_add_u64 v[164:165], s[30:31], 1, v[164:165]
	v_cvt_pk_bf16_f32 v162, v162, v163
	v_cvt_pk_bf16_f32 v163, v166, v167
	v_lshl_add_u64 v[164:165], v[164:165], 0, v[0:1]
	v_pk_mul_f32 v[152:153], v[10:11], v[152:153]
	v_pk_mul_f32 v[156:157], v[12:13], v[156:157]
	v_pk_mul_f32 v[154:155], v[6:7], v[154:155]
	s_and_b64 vcc, exec, s[42:43]
	v_pk_mul_f32 v[158:159], v[8:9], v[158:159]
	global_store_dwordx4 v[164:165], v[160:163], off
	s_cbranch_vccnz .LBB0_146
	v_pk_mul_f32 v[152:153], v[216:217], v[152:153]
	v_pk_mul_f32 v[154:155], v[220:221], v[154:155]
	v_pk_mul_f32 v[156:157], v[218:219], v[156:157]
	v_pk_mul_f32 v[158:159], v[222:223], v[158:159]

.LBB0_150:
	v_and_b32_e32 v174, 44, v160
	v_bitop3_b32 v175, v160, 63, 44 bitop3:0x6c
	v_bitop3_b32 v188, v160, 47, 44 bitop3:0x6c
	v_cvt_f32_ubyte0_e32 v193, v175
	v_sub_u32_e32 v175, 62, v174
	v_add_u32_e32 v189, -1, v188
	v_sub_u32_e32 v194, 61, v174
	v_add_u32_e32 v191, -2, v188
	v_sub_u32_e32 v195, 60, v174
	v_add_u32_e32 v174, -3, v188
	v_cvt_f32_ubyte0_e32 v192, v188
	v_cvt_f32_u32_e32 v190, v189
	v_cvt_f32_u32_e32 v188, v191
	v_cvt_f32_u32_e32 v174, v174
	v_pk_mul_f32 v[160:161], v[122:123], v[152:153]
	v_pk_mul_f32 v[162:163], v[124:125], v[156:157]
	v_pk_mul_f32 v[164:165], v[114:115], v[154:155]
	v_pk_mul_f32 v[166:167], v[116:117], v[158:159]
	s_and_b64 vcc, exec, s[42:43]
	v_cvt_f32_ubyte0_e32 v191, v175
	v_cvt_f32_ubyte0_e32 v189, v194
	v_cvt_f32_ubyte0_e32 v175, v195
	s_cbranch_vccnz .LBB0_152
	s_add_i32 s31, s11, 0xfffffc00
	s_ashr_i32 s31, s31, 7
	v_cvt_f32_i32_e32 v194, s31
	v_sub_f32_e32 v194, 0xc0a00000, v194
	v_cmp_gt_f32_e32 vcc, s9, v194
	s_and_b64 s[44:45], vcc, exec
	s_cselect_b32 s31, 0xffffffc0, 0
	v_cndmask_b32_e32 v195, 0, v200, vcc
	v_add_f32_e32 v194, v194, v195
	v_exp_f32_e32 v194, v194
	s_nop 0
	v_ldexp_f32 v194, v194, s31
	v_sub_f32_e32 v194, 1.0, v194
	v_cmp_gt_f32_e32 vcc, s7, v194
	s_and_b64 s[44:45], vcc, exec
	s_cselect_b32 s31, 32, 0
	v_ldexp_f32 v194, v194, s31
	v_log_f32_e32 v194, v194
	v_cndmask_b32_e32 v195, 0, v201, vcc
	v_sub_f32_e32 v196, v194, v195
	v_mul_f32_e32 v195, v196, v192
	v_mul_f32_e32 v194, v196, v193
	v_cmp_gt_f32_e64 s[44:45], s9, v195
	v_cmp_gt_f32_e32 vcc, s9, v194
	s_nop 0
	v_cndmask_b32_e64 v195, 0, v200, s[44:45]
	v_cndmask_b32_e32 v194, 0, v200, vcc
	v_fmac_f32_e32 v195, v196, v192
	v_fmac_f32_e32 v194, v196, v193
	v_exp_f32_e32 v195, v195
	v_exp_f32_e32 v194, v194
	v_cndmask_b32_e64 v207, 0, v202, s[44:45]
	v_cndmask_b32_e32 v197, 0, v202, vcc
	v_ldexp_f32 v208, v195, v207
	v_mul_f32_e32 v195, v196, v191
	v_ldexp_f32 v194, v194, v197
	v_cmp_gt_f32_e32 vcc, s9, v195
	v_mul_f32_e32 v197, v196, v190
	v_cmp_gt_f32_e64 s[44:45], s9, v197
	v_cndmask_b32_e32 v195, 0, v200, vcc
	v_fmac_f32_e32 v195, v196, v191
	v_cndmask_b32_e64 v197, 0, v200, s[44:45]
	v_exp_f32_e32 v195, v195
	v_fmac_f32_e32 v197, v196, v190
	v_exp_f32_e32 v197, v197
	v_cndmask_b32_e32 v207, 0, v202, vcc
	v_ldexp_f32 v195, v195, v207
	v_cndmask_b32_e64 v207, 0, v202, s[44:45]
	v_ldexp_f32 v209, v197, v207
	v_mul_f32_e32 v197, v196, v189
	v_cmp_gt_f32_e32 vcc, s9, v197
	v_mul_f32_e32 v207, v196, v188
	v_cmp_gt_f32_e64 s[44:45], s9, v207
	v_cndmask_b32_e32 v197, 0, v200, vcc
	v_fmac_f32_e32 v197, v196, v189
	v_cndmask_b32_e64 v207, 0, v200, s[44:45]
	v_exp_f32_e32 v197, v197
	v_fmac_f32_e32 v207, v196, v188
	v_exp_f32_e32 v207, v207
	v_cndmask_b32_e32 v210, 0, v202, vcc
	v_ldexp_f32 v210, v197, v210
	v_cndmask_b32_e64 v197, 0, v202, s[44:45]
	v_ldexp_f32 v212, v207, v197
	v_mul_f32_e32 v197, v196, v175
	v_cmp_gt_f32_e32 vcc, s9, v197
	v_mul_f32_e32 v207, v196, v174
	v_cmp_gt_f32_e64 s[44:45], s9, v207
	v_cndmask_b32_e32 v197, 0, v200, vcc
	v_fmac_f32_e32 v197, v196, v175
	v_cndmask_b32_e64 v207, 0, v200, s[44:45]
	v_exp_f32_e32 v197, v197
	v_fmac_f32_e32 v207, v196, v174
	v_exp_f32_e32 v196, v207
	v_cndmask_b32_e32 v207, 0, v202, vcc
	v_ldexp_f32 v211, v197, v207
	v_cndmask_b32_e64 v197, 0, v202, s[44:45]
	v_ldexp_f32 v213, v196, v197
	v_pk_mul_f32 v[160:161], v[194:195], v[160:161]
	v_pk_mul_f32 v[162:163], v[210:211], v[162:163]
	v_pk_mul_f32 v[164:165], v[208:209], v[164:165]
	v_pk_mul_f32 v[166:167], v[212:213], v[166:167]
	v_mov_b32_e32 v216, v194
	v_mov_b32_e32 v217, v195
	v_mov_b32_e32 v218, v210
	v_mov_b32_e32 v219, v211
	v_mov_b32_e32 v220, v208
	v_mov_b32_e32 v221, v209
	v_mov_b32_e32 v222, v212
	v_mov_b32_e32 v223, v213
.LBB0_152:
	s_mulk_i32 s19, 0xc00
	s_add_i32 s19, s19, s22
	v_cvt_pk_bf16_f32 v160, v160, v161
	v_cvt_pk_bf16_f32 v161, v162, v163
	v_cvt_pk_bf16_f32 v162, v164, v165
	v_add_u32_e32 v164, s19, v176
	s_ashr_i32 s31, s30, 31
	v_mad_i64_i32 v[164:165], s[44:45], v164, s80, v[134:135]
	v_lshl_add_u64 v[164:165], s[30:31], 1, v[164:165]
	v_cvt_pk_bf16_f32 v163, v166, v167
	v_lshl_add_u64 v[164:165], v[164:165], 0, v[0:1]
	global_store_dwordx4 v[164:165], v[160:163], off
	v_pk_mul_f32 v[164:165], v[108:109], v[156:157]
	s_and_b64 vcc, exec, s[42:43]
	v_pk_mul_f32 v[160:161], v[106:107], v[152:153]
	v_pk_mul_f32 v[162:163], v[94:95], v[154:155]
	v_pk_mul_f32 v[166:167], v[96:97], v[158:159]
	s_cbranch_vccnz .LBB0_154
	v_pk_mul_f32 v[160:161], v[216:217], v[160:161]
	v_pk_mul_f32 v[164:165], v[218:219], v[164:165]
	v_pk_mul_f32 v[162:163], v[220:221], v[162:163]
	v_pk_mul_f32 v[166:167], v[222:223], v[166:167]
.LBB0_154:
	v_cvt_pk_bf16_f32 v160, v160, v161
	v_cvt_pk_bf16_f32 v161, v164, v165
	v_add_u32_e32 v164, s19, v177
	v_mad_i64_i32 v[164:165], s[44:45], v164, s80, v[134:135]
	v_lshl_add_u64 v[164:165], s[30:31], 1, v[164:165]
	v_cvt_pk_bf16_f32 v162, v162, v163
	v_cvt_pk_bf16_f32 v163, v166, v167
	v_lshl_add_u64 v[164:165], v[164:165], 0, v[0:1]
	global_store_dwordx4 v[164:165], v[160:163], off
	v_pk_mul_f32 v[164:165], v[92:93], v[156:157]
	s_and_b64 vcc, exec, s[42:43]
	v_pk_mul_f32 v[160:161], v[90:91], v[152:153]
	v_pk_mul_f32 v[162:163], v[82:83], v[154:155]
	v_pk_mul_f32 v[166:167], v[84:85], v[158:159]
	s_cbranch_vccnz .LBB0_156
	v_pk_mul_f32 v[160:161], v[216:217], v[160:161]
	v_pk_mul_f32 v[164:165], v[218:219], v[164:165]
	v_pk_mul_f32 v[162:163], v[220:221], v[162:163]
	v_pk_mul_f32 v[166:167], v[222:223], v[166:167]
.LBB0_156:
	v_cvt_pk_bf16_f32 v160, v160, v161
	v_cvt_pk_bf16_f32 v161, v164, v165
	v_add_u32_e32 v164, s19, v178
	v_mad_i64_i32 v[164:165], s[44:45], v164, s80, v[134:135]
	v_lshl_add_u64 v[164:165], s[30:31], 1, v[164:165]
	v_cvt_pk_bf16_f32 v162, v162, v163
	v_cvt_pk_bf16_f32 v163, v166, v167
	v_lshl_add_u64 v[164:165], v[164:165], 0, v[0:1]
	global_store_dwordx4 v[164:165], v[160:163], off
	v_pk_mul_f32 v[164:165], v[76:77], v[156:157]
	s_and_b64 vcc, exec, s[42:43]
	v_pk_mul_f32 v[160:161], v[74:75], v[152:153]
	v_pk_mul_f32 v[162:163], v[70:71], v[154:155]
	v_pk_mul_f32 v[166:167], v[72:73], v[158:159]
	s_cbranch_vccnz .LBB0_158
	v_pk_mul_f32 v[160:161], v[216:217], v[160:161]
	v_pk_mul_f32 v[164:165], v[218:219], v[164:165]
	v_pk_mul_f32 v[162:163], v[220:221], v[162:163]
	v_pk_mul_f32 v[166:167], v[222:223], v[166:167]
.LBB0_158:
	v_cvt_pk_bf16_f32 v160, v160, v161
	v_cvt_pk_bf16_f32 v161, v164, v165
	v_add_u32_e32 v164, s19, v179
	v_mad_i64_i32 v[164:165], s[44:45], v164, s80, v[134:135]
	v_lshl_add_u64 v[164:165], s[30:31], 1, v[164:165]
	v_cvt_pk_bf16_f32 v162, v162, v163
	v_cvt_pk_bf16_f32 v163, v166, v167
	v_lshl_add_u64 v[164:165], v[164:165], 0, v[0:1]
	global_store_dwordx4 v[164:165], v[160:163], off
	v_pk_mul_f32 v[164:165], v[60:61], v[156:157]
	s_and_b64 vcc, exec, s[42:43]
	v_pk_mul_f32 v[160:161], v[58:59], v[152:153]
	v_pk_mul_f32 v[162:163], v[54:55], v[154:155]
	v_pk_mul_f32 v[166:167], v[56:57], v[158:159]
	s_cbranch_vccnz .LBB0_160
	s_add_i32 s11, s18, 0xfffffc00
	s_ashr_i32 s11, s11, 7
	v_cvt_f32_i32_e32 v176, s11
	v_sub_f32_e32 v176, 0xc0a00000, v176
	v_cmp_gt_f32_e32 vcc, s9, v176
	s_and_b64 s[44:45], vcc, exec
	s_cselect_b32 s11, 0xffffffc0, 0
	v_cndmask_b32_e32 v177, 0, v200, vcc
	v_add_f32_e32 v176, v176, v177
	v_exp_f32_e32 v176, v176
	s_nop 0
	v_ldexp_f32 v176, v176, s11
	v_sub_f32_e32 v176, 1.0, v176
	v_cmp_gt_f32_e32 vcc, s7, v176
	s_and_b64 s[44:45], vcc, exec
	s_cselect_b32 s11, 32, 0
	v_ldexp_f32 v176, v176, s11
	v_log_f32_e32 v176, v176
	v_cndmask_b32_e32 v177, 0, v201, vcc
	v_sub_f32_e32 v195, v176, v177
	v_mul_f32_e32 v176, v195, v193
	v_mul_f32_e32 v177, v195, v192
	v_cmp_gt_f32_e32 vcc, s9, v176
	v_cmp_gt_f32_e64 s[44:45], s9, v177
	v_mul_f32_e32 v196, v195, v188
	v_cndmask_b32_e32 v176, 0, v200, vcc
	v_cndmask_b32_e64 v177, 0, v200, s[44:45]
	v_fmac_f32_e32 v176, v195, v193
	v_fmac_f32_e32 v177, v195, v192
	v_exp_f32_e32 v176, v176
	v_exp_f32_e32 v177, v177
	v_cndmask_b32_e32 v178, 0, v202, vcc
	v_cndmask_b32_e64 v179, 0, v202, s[44:45]
	v_ldexp_f32 v176, v176, v178
	v_ldexp_f32 v178, v177, v179
	v_mul_f32_e32 v177, v195, v191
	v_cmp_gt_f32_e32 vcc, s9, v177
	v_mul_f32_e32 v179, v195, v190
	v_cmp_gt_f32_e64 s[44:45], s9, v179
	v_cndmask_b32_e32 v177, 0, v200, vcc
	v_fmac_f32_e32 v177, v195, v191
	v_cndmask_b32_e64 v179, 0, v200, s[44:45]
	v_exp_f32_e32 v177, v177
	v_fmac_f32_e32 v179, v195, v190
	v_exp_f32_e32 v179, v179
	v_cndmask_b32_e32 v194, 0, v202, vcc
	v_ldexp_f32 v177, v177, v194
	v_cndmask_b32_e64 v194, 0, v202, s[44:45]
	v_ldexp_f32 v179, v179, v194
	v_mul_f32_e32 v194, v195, v189
	v_cmp_gt_f32_e32 vcc, s9, v194
	v_cmp_gt_f32_e64 s[44:45], s9, v196
	v_pk_mul_f32 v[160:161], v[176:177], v[160:161]
	v_cndmask_b32_e32 v194, 0, v200, vcc
	v_fmac_f32_e32 v194, v195, v189
	v_cndmask_b32_e64 v196, 0, v200, s[44:45]
	v_exp_f32_e32 v194, v194
	v_fmac_f32_e32 v196, v195, v188
	v_exp_f32_e32 v196, v196
	v_cndmask_b32_e32 v197, 0, v202, vcc
	v_ldexp_f32 v194, v194, v197
	v_cndmask_b32_e64 v197, 0, v202, s[44:45]
	v_ldexp_f32 v208, v196, v197
	v_mul_f32_e32 v196, v195, v175
	v_cmp_gt_f32_e32 vcc, s9, v196
	v_mul_f32_e32 v197, v195, v174
	v_cmp_gt_f32_e64 s[44:45], s9, v197
	v_cndmask_b32_e32 v196, 0, v200, vcc
	v_fmac_f32_e32 v196, v195, v175
	v_cndmask_b32_e64 v197, 0, v200, s[44:45]
	v_exp_f32_e32 v196, v196
	v_fmac_f32_e32 v197, v195, v174
	v_exp_f32_e32 v197, v197
	v_cndmask_b32_e32 v195, 0, v202, vcc
	v_ldexp_f32 v195, v196, v195
	v_cndmask_b32_e64 v196, 0, v202, s[44:45]
	v_ldexp_f32 v209, v197, v196
	v_pk_mul_f32 v[164:165], v[194:195], v[164:165]
	v_pk_mul_f32 v[162:163], v[178:179], v[162:163]
	v_pk_mul_f32 v[166:167], v[208:209], v[166:167]
	v_mov_b32_e32 v216, v176
	v_mov_b32_e32 v217, v177
	v_mov_b32_e32 v218, v194
	v_mov_b32_e32 v219, v195
	v_mov_b32_e32 v220, v178
	v_mov_b32_e32 v221, v179
	v_mov_b32_e32 v222, v208
	v_mov_b32_e32 v223, v209
.LBB0_160:
	v_cvt_pk_bf16_f32 v160, v160, v161
	v_cvt_pk_bf16_f32 v161, v164, v165
	v_add_u32_e32 v164, s19, v183
	v_mad_i64_i32 v[164:165], s[44:45], v164, s80, v[134:135]
	v_lshl_add_u64 v[164:165], s[30:31], 1, v[164:165]
	v_cvt_pk_bf16_f32 v162, v162, v163
	v_cvt_pk_bf16_f32 v163, v166, v167
	v_lshl_add_u64 v[164:165], v[164:165], 0, v[0:1]
	global_store_dwordx4 v[164:165], v[160:163], off
	v_pk_mul_f32 v[164:165], v[28:29], v[156:157]
	s_and_b64 vcc, exec, s[42:43]
	v_pk_mul_f32 v[160:161], v[26:27], v[152:153]
	v_pk_mul_f32 v[162:163], v[18:19], v[154:155]
	v_pk_mul_f32 v[166:167], v[20:21], v[158:159]
	s_cbranch_vccnz .LBB0_162
	v_pk_mul_f32 v[160:161], v[216:217], v[160:161]
	v_pk_mul_f32 v[164:165], v[218:219], v[164:165]
	v_pk_mul_f32 v[162:163], v[220:221], v[162:163]
	v_pk_mul_f32 v[166:167], v[222:223], v[166:167]
.LBB0_162:
	v_cvt_pk_bf16_f32 v160, v160, v161
	v_cvt_pk_bf16_f32 v161, v164, v165
	v_add_u32_e32 v164, s19, v184
	v_mad_i64_i32 v[164:165], s[44:45], v164, s80, v[134:135]
	v_lshl_add_u64 v[164:165], s[30:31], 1, v[164:165]
	v_cvt_pk_bf16_f32 v162, v162, v163
	v_cvt_pk_bf16_f32 v163, v166, v167
	v_lshl_add_u64 v[164:165], v[164:165], 0, v[0:1]
	global_store_dwordx4 v[164:165], v[160:163], off
	v_pk_mul_f32 v[164:165], v[52:53], v[156:157]
	s_and_b64 vcc, exec, s[42:43]
	v_pk_mul_f32 v[160:161], v[50:51], v[152:153]
	v_pk_mul_f32 v[162:163], v[42:43], v[154:155]
	v_pk_mul_f32 v[166:167], v[44:45], v[158:159]
	s_cbranch_vccnz .LBB0_164
	v_pk_mul_f32 v[160:161], v[216:217], v[160:161]
	v_pk_mul_f32 v[164:165], v[218:219], v[164:165]
	v_pk_mul_f32 v[162:163], v[220:221], v[162:163]
	v_pk_mul_f32 v[166:167], v[222:223], v[166:167]
.LBB0_164:
	v_cvt_pk_bf16_f32 v160, v160, v161
	v_cvt_pk_bf16_f32 v161, v164, v165
	v_add_u32_e32 v164, s19, v187
	v_mad_i64_i32 v[164:165], s[44:45], v164, s80, v[134:135]
	v_lshl_add_u64 v[164:165], s[30:31], 1, v[164:165]
	v_cvt_pk_bf16_f32 v162, v162, v163
	v_cvt_pk_bf16_f32 v163, v166, v167
	v_lshl_add_u64 v[164:165], v[164:165], 0, v[0:1]
	v_pk_mul_f32 v[152:153], v[34:35], v[152:153]
	v_pk_mul_f32 v[156:157], v[36:37], v[156:157]
	v_pk_mul_f32 v[154:155], v[30:31], v[154:155]
	s_and_b64 vcc, exec, s[42:43]
	v_pk_mul_f32 v[158:159], v[32:33], v[158:159]
	global_store_dwordx4 v[164:165], v[160:163], off
	s_cbranch_vccnz .LBB0_166
	v_pk_mul_f32 v[152:153], v[216:217], v[152:153]
	v_pk_mul_f32 v[154:155], v[220:221], v[154:155]
	v_pk_mul_f32 v[156:157], v[218:219], v[156:157]
	v_pk_mul_f32 v[158:159], v[222:223], v[158:159]
